# grid barrier: non-leader workgroups poll the global generation word instead of the per-XCC generation (one hop fewer)
# baseline (speedup 1.0000x reference)
; __device__ __forceinline__ unsigned xb_ld(unsigned* p)              { return __hip_atomic_load(p, __ATOMIC_RELAXED, __HIP_MEMORY_SCOPE_AGENT); }
; __device__ __forceinline__ unsigned xb_add(unsigned* p, unsigned v) { return __hip_atomic_fetch_add(p, v, __ATOMIC_RELAXED, __HIP_MEMORY_SCOPE_AGENT); }
; #define XB_SPIN(cond, bar) do { unsigned _sp = 0; while (cond) { __builtin_amdgcn_s_sleep(1); \
;     if ((++_sp & 255u) == 0u) { if (xb_ld(&(bar)[XB_TMO])) break; if (_sp > XB_SPIN_CAP) { atomicAdd(&(bar)[XB_TMO], 1u); break; } } } } while (0)
; __device__ __forceinline__ void xcd_barrier(const XcdBarrier& b) {
;     ...
;     const unsigned old = xb_add(&bar[XB_XSUB(bx)], 1u);
;     const unsigned gen = old / nloc;
;     if (old + 1u == (gen + 1u) * nloc) {
;       __builtin_amdgcn_fence(__ATOMIC_RELEASE, "agent");
;       asm volatile("s_waitcnt vmcnt(0)" ::: "memory");
;       const unsigned og = xb_add(&bar[XB_TOP], 1u);
;       const unsigned tg = og / nx;
;       if (og + 1u == (tg + 1u) * nx) xb_add(&bar[XB_TOPGEN], 1u);
;       else XB_SPIN(xb_ld(&bar[XB_TOPGEN]) == tg, bar);
;       __builtin_amdgcn_fence(__ATOMIC_ACQUIRE, "agent");
;       xb_add(&bar[XB_XGEN(bx)], 1u);
;       asm volatile("s_waitcnt vmcnt(0)" ::: "memory");
;     } else {
;       XB_SPIN(xb_ld(&bar[XB_XGEN(bx)]) == gen, bar);
.LBB0_116:
	s_or_b64 exec, exec, s[10:11]
	v_cvt_f32_u32_e32 v5, v3
	s_waitcnt vmcnt(0)
	v_readfirstlane_b32 s4, v4
	v_sub_u32_e32 v4, 0, v3
	v_rcp_iflag_f32_e32 v5, v5
	v_add_u32_e32 v6, s4, v1
	v_mul_f32_e32 v5, 0x4f7ffffe, v5
	v_cvt_u32_f32_e32 v5, v5
	v_mul_lo_u32 v1, v4, v5
	v_mul_hi_u32 v1, v5, v1
	v_add_u32_e32 v1, v5, v1
	v_mul_hi_u32 v1, v6, v1
	v_mul_lo_u32 v4, v1, v3
	v_sub_u32_e32 v4, v6, v4
	v_add_u32_e32 v5, 1, v1
	v_cmp_ge_u32_e32 vcc, v4, v3
	s_nop 1
	v_cndmask_b32_e32 v1, v1, v5, vcc
	v_sub_u32_e32 v5, v4, v3
	v_cndmask_b32_e32 v4, v4, v5, vcc
	v_add_u32_e32 v5, 1, v1
	v_cmp_ge_u32_e32 vcc, v4, v3
	v_add_u32_e32 v4, 1, v6
	s_nop 0
	v_cndmask_b32_e32 v1, v1, v5, vcc
	v_mul_lo_u32 v5, v3, v1
	v_add_u32_e32 v3, v5, v3
	v_cmp_ne_u32_e32 vcc, v4, v3
	s_and_saveexec_b64 s[4:5], vcc
	s_xor_b64 s[8:9], exec, s[4:5]
	s_cbranch_execz .LBB0_130
	s_movk_i32 s4, 0xd40
	s_mov_b32 s5, 0
	s_lshl_b64 s[4:5], s[4:5], 2
	v_readlane_b32 s10, v240, 2
	v_readlane_b32 s11, v240, 3
	s_add_u32 s14, s10, s4
	s_addc_u32 s15, s11, s5
	s_waitcnt lgkmcnt(0)
	v_mov_b32_e32 v2, 0
	global_load_dword v3, v2, s[14:15] sc1
	s_waitcnt vmcnt(0)
	v_cmp_eq_u32_e32 vcc, v3, v1
	s_and_saveexec_b64 s[10:11], vcc
	s_cbranch_execz .LBB0_129
	s_add_u32 s12, s34, 0x1fbfc200
	s_addc_u32 s13, s35, 0
	s_mov_b32 s4, 1
	s_mov_b64 s[16:17], 0
	s_branch .LBB0_120

; __device__ __forceinline__ unsigned xb_ld(unsigned* p)              { return __hip_atomic_load(p, __ATOMIC_RELAXED, __HIP_MEMORY_SCOPE_AGENT); }
; __device__ __forceinline__ unsigned xb_add(unsigned* p, unsigned v) { return __hip_atomic_fetch_add(p, v, __ATOMIC_RELAXED, __HIP_MEMORY_SCOPE_AGENT); }
; #define XB_SPIN(cond, bar) do { unsigned _sp = 0; while (cond) { __builtin_amdgcn_s_sleep(1); \
;     if ((++_sp & 255u) == 0u) { if (xb_ld(&(bar)[XB_TMO])) break; if (_sp > XB_SPIN_CAP) { atomicAdd(&(bar)[XB_TMO], 1u); break; } } } } while (0)
; __device__ __forceinline__ void xcd_barrier(const XcdBarrier& b) {
;     ...
;     const unsigned old = xb_add(&bar[XB_XSUB(bx)], 1u);
;     const unsigned gen = old / nloc;
;     if (old + 1u == (gen + 1u) * nloc) {
;       __builtin_amdgcn_fence(__ATOMIC_RELEASE, "agent");
;       asm volatile("s_waitcnt vmcnt(0)" ::: "memory");
;       const unsigned og = xb_add(&bar[XB_TOP], 1u);
;       const unsigned tg = og / nx;
;       if (og + 1u == (tg + 1u) * nx) xb_add(&bar[XB_TOPGEN], 1u);
;       else XB_SPIN(xb_ld(&bar[XB_TOPGEN]) == tg, bar);
;       __builtin_amdgcn_fence(__ATOMIC_ACQUIRE, "agent");
;       xb_add(&bar[XB_XGEN(bx)], 1u);
;       asm volatile("s_waitcnt vmcnt(0)" ::: "memory");
;     } else {
;       XB_SPIN(xb_ld(&bar[XB_XGEN(bx)]) == gen, bar);
.LBB0_434:
	s_or_b64 exec, exec, s[8:9]
	v_cvt_f32_u32_e32 v4, v2
	s_waitcnt vmcnt(0)
	v_readfirstlane_b32 s4, v3
	v_sub_u32_e32 v3, 0, v2
	v_rcp_iflag_f32_e32 v4, v4
	v_add_u32_e32 v5, s4, v0
	v_mul_f32_e32 v4, 0x4f7ffffe, v4
	v_cvt_u32_f32_e32 v4, v4
	v_mul_lo_u32 v0, v3, v4
	v_mul_hi_u32 v0, v4, v0
	v_add_u32_e32 v0, v4, v0
	v_mul_hi_u32 v0, v5, v0
	v_mul_lo_u32 v3, v0, v2
	v_sub_u32_e32 v3, v5, v3
	v_add_u32_e32 v4, 1, v0
	v_cmp_ge_u32_e32 vcc, v3, v2
	s_nop 1
	v_cndmask_b32_e32 v0, v0, v4, vcc
	v_sub_u32_e32 v4, v3, v2
	v_cndmask_b32_e32 v3, v3, v4, vcc
	v_add_u32_e32 v4, 1, v0
	v_cmp_ge_u32_e32 vcc, v3, v2
	v_add_u32_e32 v3, 1, v5
	s_nop 0
	v_cndmask_b32_e32 v0, v0, v4, vcc
	v_mul_lo_u32 v4, v2, v0
	v_add_u32_e32 v2, v4, v2
	v_cmp_ne_u32_e32 vcc, v3, v2
	s_and_saveexec_b64 s[4:5], vcc
	s_xor_b64 s[6:7], exec, s[4:5]
	s_cbranch_execz .LBB0_448
	s_movk_i32 s4, 0xd40
	s_mov_b32 s5, 0
	s_lshl_b64 s[4:5], s[4:5], 2
	v_readlane_b32 s8, v240, 2
	v_readlane_b32 s9, v240, 3
	s_add_u32 s12, s8, s4
	s_addc_u32 s13, s9, s5
	s_waitcnt lgkmcnt(0)
	v_mov_b32_e32 v1, 0
	global_load_dword v2, v1, s[12:13] sc1
	s_waitcnt vmcnt(0)
	v_cmp_eq_u32_e32 vcc, v2, v0
	s_and_saveexec_b64 s[8:9], vcc
	s_cbranch_execz .LBB0_447
	s_add_u32 s10, s34, 0x1fbfc200
	s_addc_u32 s11, s35, 0
	s_mov_b32 s4, 1
	s_mov_b64 s[14:15], 0
	s_branch .LBB0_438

; __device__ __forceinline__ unsigned xb_ld(unsigned* p)              { return __hip_atomic_load(p, __ATOMIC_RELAXED, __HIP_MEMORY_SCOPE_AGENT); }
; __device__ __forceinline__ unsigned xb_add(unsigned* p, unsigned v) { return __hip_atomic_fetch_add(p, v, __ATOMIC_RELAXED, __HIP_MEMORY_SCOPE_AGENT); }
; #define XB_SPIN(cond, bar) do { unsigned _sp = 0; while (cond) { __builtin_amdgcn_s_sleep(1); \
;     if ((++_sp & 255u) == 0u) { if (xb_ld(&(bar)[XB_TMO])) break; if (_sp > XB_SPIN_CAP) { atomicAdd(&(bar)[XB_TMO], 1u); break; } } } } while (0)
; __device__ __forceinline__ void xcd_barrier(const XcdBarrier& b) {
;     ...
;     const unsigned old = xb_add(&bar[XB_XSUB(bx)], 1u);
;     const unsigned gen = old / nloc;
;     if (old + 1u == (gen + 1u) * nloc) {
;       __builtin_amdgcn_fence(__ATOMIC_RELEASE, "agent");
;       asm volatile("s_waitcnt vmcnt(0)" ::: "memory");
;       const unsigned og = xb_add(&bar[XB_TOP], 1u);
;       const unsigned tg = og / nx;
;       if (og + 1u == (tg + 1u) * nx) xb_add(&bar[XB_TOPGEN], 1u);
;       else XB_SPIN(xb_ld(&bar[XB_TOPGEN]) == tg, bar);
;       __builtin_amdgcn_fence(__ATOMIC_ACQUIRE, "agent");
;       xb_add(&bar[XB_XGEN(bx)], 1u);
;       asm volatile("s_waitcnt vmcnt(0)" ::: "memory");
;     } else {
;       XB_SPIN(xb_ld(&bar[XB_XGEN(bx)]) == gen, bar);
.LBB0_789:
	s_or_b64 exec, exec, s[10:11]
	v_cvt_f32_u32_e32 v4, v2
	s_waitcnt vmcnt(0)
	v_readfirstlane_b32 s8, v3
	v_sub_u32_e32 v3, 0, v2
	v_rcp_iflag_f32_e32 v4, v4
	v_add_u32_e32 v5, s8, v1
	v_mul_f32_e32 v4, 0x4f7ffffe, v4
	v_cvt_u32_f32_e32 v4, v4
	v_mul_lo_u32 v1, v3, v4
	v_mul_hi_u32 v1, v4, v1
	v_add_u32_e32 v1, v4, v1
	v_mul_hi_u32 v1, v5, v1
	v_mul_lo_u32 v3, v1, v2
	v_sub_u32_e32 v3, v5, v3
	v_add_u32_e32 v4, 1, v1
	v_cmp_ge_u32_e32 vcc, v3, v2
	s_nop 1
	v_cndmask_b32_e32 v1, v1, v4, vcc
	v_sub_u32_e32 v4, v3, v2
	v_cndmask_b32_e32 v3, v3, v4, vcc
	v_add_u32_e32 v4, 1, v1
	v_cmp_ge_u32_e32 vcc, v3, v2
	v_add_u32_e32 v3, 1, v5
	s_nop 0
	v_cndmask_b32_e32 v1, v1, v4, vcc
	v_mul_lo_u32 v4, v2, v1
	v_add_u32_e32 v2, v4, v2
	v_cmp_ne_u32_e32 vcc, v3, v2
	s_and_saveexec_b64 s[8:9], vcc
	s_xor_b64 s[8:9], exec, s[8:9]
	s_cbranch_execz .LBB0_803
	s_movk_i32 s74, 0xd40
	s_lshl_b64 s[10:11], s[74:75], 2
	v_readlane_b32 s12, v240, 2
	v_readlane_b32 s13, v240, 3
	s_add_u32 s12, s12, s10
	s_addc_u32 s13, s13, s11
	s_waitcnt lgkmcnt(0)
	s_nop 1
	global_load_dword v0, v97, s[12:13] sc1
	s_waitcnt vmcnt(0)
	v_cmp_eq_u32_e32 vcc, v0, v1
	s_and_saveexec_b64 s[10:11], vcc
	s_cbranch_execz .LBB0_802
	s_mov_b32 s36, 1
	s_mov_b64 s[82:83], 0
	s_branch .LBB0_793

; __device__ __forceinline__ unsigned xb_ld(unsigned* p)              { return __hip_atomic_load(p, __ATOMIC_RELAXED, __HIP_MEMORY_SCOPE_AGENT); }
; __device__ __forceinline__ unsigned xb_add(unsigned* p, unsigned v) { return __hip_atomic_fetch_add(p, v, __ATOMIC_RELAXED, __HIP_MEMORY_SCOPE_AGENT); }
; #define XB_SPIN(cond, bar) do { unsigned _sp = 0; while (cond) { __builtin_amdgcn_s_sleep(1); \
;     if ((++_sp & 255u) == 0u) { if (xb_ld(&(bar)[XB_TMO])) break; if (_sp > XB_SPIN_CAP) { atomicAdd(&(bar)[XB_TMO], 1u); break; } } } } while (0)
; __device__ __forceinline__ void xcd_barrier(const XcdBarrier& b) {
;     ...
;     const unsigned old = xb_add(&bar[XB_XSUB(bx)], 1u);
;     const unsigned gen = old / nloc;
;     if (old + 1u == (gen + 1u) * nloc) {
;       __builtin_amdgcn_fence(__ATOMIC_RELEASE, "agent");
;       asm volatile("s_waitcnt vmcnt(0)" ::: "memory");
;       const unsigned og = xb_add(&bar[XB_TOP], 1u);
;       const unsigned tg = og / nx;
;       if (og + 1u == (tg + 1u) * nx) xb_add(&bar[XB_TOPGEN], 1u);
;       else XB_SPIN(xb_ld(&bar[XB_TOPGEN]) == tg, bar);
;       __builtin_amdgcn_fence(__ATOMIC_ACQUIRE, "agent");
;       xb_add(&bar[XB_XGEN(bx)], 1u);
;       asm volatile("s_waitcnt vmcnt(0)" ::: "memory");
;     } else {
;       XB_SPIN(xb_ld(&bar[XB_XGEN(bx)]) == gen, bar);
.LBB0_926:
	s_or_b64 exec, exec, s[10:11]
	v_cvt_f32_u32_e32 v4, v2
	s_waitcnt vmcnt(0)
	v_readfirstlane_b32 s3, v3
	v_sub_u32_e32 v3, 0, v2
	v_rcp_iflag_f32_e32 v4, v4
	v_add_u32_e32 v5, s3, v1
	v_mul_f32_e32 v4, 0x4f7ffffe, v4
	v_cvt_u32_f32_e32 v4, v4
	v_mul_lo_u32 v1, v3, v4
	v_mul_hi_u32 v1, v4, v1
	v_add_u32_e32 v1, v4, v1
	v_mul_hi_u32 v1, v5, v1
	v_mul_lo_u32 v3, v1, v2
	v_sub_u32_e32 v3, v5, v3
	v_add_u32_e32 v4, 1, v1
	v_cmp_ge_u32_e32 vcc, v3, v2
	s_nop 1
	v_cndmask_b32_e32 v1, v1, v4, vcc
	v_sub_u32_e32 v4, v3, v2
	v_cndmask_b32_e32 v3, v3, v4, vcc
	v_add_u32_e32 v4, 1, v1
	v_cmp_ge_u32_e32 vcc, v3, v2
	v_add_u32_e32 v3, 1, v5
	s_nop 0
	v_cndmask_b32_e32 v1, v1, v4, vcc
	v_mul_lo_u32 v4, v2, v1
	v_add_u32_e32 v2, v4, v2
	v_cmp_ne_u32_e32 vcc, v3, v2
	s_and_saveexec_b64 s[4:5], vcc
	s_xor_b64 s[8:9], exec, s[4:5]
	s_cbranch_execz .LBB0_940
	s_movk_i32 s4, 0xd40
	s_mov_b32 s5, 0
	s_lshl_b64 s[4:5], s[4:5], 2
	v_readlane_b32 s10, v240, 2
	v_readlane_b32 s11, v240, 3
	s_add_u32 s12, s10, s4
	s_addc_u32 s13, s11, s5
	s_waitcnt lgkmcnt(0)
	v_mov_b32_e32 v0, 0
	global_load_dword v2, v0, s[12:13] sc1
	s_waitcnt vmcnt(0)
	v_cmp_eq_u32_e32 vcc, v2, v1
	s_and_saveexec_b64 s[10:11], vcc
	s_cbranch_execz .LBB0_939
	s_mov_b32 s3, 1
	s_mov_b64 s[14:15], 0
	s_branch .LBB0_930

; __device__ __forceinline__ unsigned xb_ld(unsigned* p)              { return __hip_atomic_load(p, __ATOMIC_RELAXED, __HIP_MEMORY_SCOPE_AGENT); }
; __device__ __forceinline__ unsigned xb_add(unsigned* p, unsigned v) { return __hip_atomic_fetch_add(p, v, __ATOMIC_RELAXED, __HIP_MEMORY_SCOPE_AGENT); }
; #define XB_SPIN(cond, bar) do { unsigned _sp = 0; while (cond) { __builtin_amdgcn_s_sleep(1); \
;     if ((++_sp & 255u) == 0u) { if (xb_ld(&(bar)[XB_TMO])) break; if (_sp > XB_SPIN_CAP) { atomicAdd(&(bar)[XB_TMO], 1u); break; } } } } while (0)
; __device__ __forceinline__ void xcd_barrier(const XcdBarrier& b) {
;     ...
;     const unsigned old = xb_add(&bar[XB_XSUB(bx)], 1u);
;     const unsigned gen = old / nloc;
;     if (old + 1u == (gen + 1u) * nloc) {
;       __builtin_amdgcn_fence(__ATOMIC_RELEASE, "agent");
;       asm volatile("s_waitcnt vmcnt(0)" ::: "memory");
;       const unsigned og = xb_add(&bar[XB_TOP], 1u);
;       const unsigned tg = og / nx;
;       if (og + 1u == (tg + 1u) * nx) xb_add(&bar[XB_TOPGEN], 1u);
;       else XB_SPIN(xb_ld(&bar[XB_TOPGEN]) == tg, bar);
;       __builtin_amdgcn_fence(__ATOMIC_ACQUIRE, "agent");
;       xb_add(&bar[XB_XGEN(bx)], 1u);
;       asm volatile("s_waitcnt vmcnt(0)" ::: "memory");
;     } else {
;       XB_SPIN(xb_ld(&bar[XB_XGEN(bx)]) == gen, bar);
.LBB0_1431:
	s_or_b64 exec, exec, s[10:11]
	v_cvt_f32_u32_e32 v5, v3
	s_waitcnt vmcnt(0)
	v_readfirstlane_b32 s8, v4
	v_sub_u32_e32 v4, 0, v3
	v_rcp_iflag_f32_e32 v5, v5
	v_add_u32_e32 v6, s8, v0
	v_mul_f32_e32 v5, 0x4f7ffffe, v5
	v_cvt_u32_f32_e32 v5, v5
	v_mul_lo_u32 v0, v4, v5
	v_mul_hi_u32 v0, v5, v0
	v_add_u32_e32 v0, v5, v0
	v_mul_hi_u32 v0, v6, v0
	v_mul_lo_u32 v4, v0, v3
	v_sub_u32_e32 v4, v6, v4
	v_add_u32_e32 v5, 1, v0
	v_cmp_ge_u32_e32 vcc, v4, v3
	s_nop 1
	v_cndmask_b32_e32 v0, v0, v5, vcc
	v_sub_u32_e32 v5, v4, v3
	v_cndmask_b32_e32 v4, v4, v5, vcc
	v_add_u32_e32 v5, 1, v0
	v_cmp_ge_u32_e32 vcc, v4, v3
	v_add_u32_e32 v4, 1, v6
	s_nop 0
	v_cndmask_b32_e32 v0, v0, v5, vcc
	v_mul_lo_u32 v5, v3, v0
	v_add_u32_e32 v3, v5, v3
	v_cmp_ne_u32_e32 vcc, v4, v3
	s_and_saveexec_b64 s[8:9], vcc
	s_xor_b64 s[8:9], exec, s[8:9]
	s_cbranch_execz .LBB0_1445
	s_movk_i32 s96, 0xd40
	s_lshl_b64 s[10:11], s[96:97], 2
	v_readlane_b32 s12, v240, 2
	v_readlane_b32 s13, v240, 3
	s_add_u32 s12, s12, s10
	s_addc_u32 s13, s13, s11
	s_waitcnt lgkmcnt(0)
	s_nop 1
	global_load_dword v2, v1, s[12:13] sc1
	s_waitcnt vmcnt(0)
	v_cmp_eq_u32_e32 vcc, v2, v0
	s_and_saveexec_b64 s[10:11], vcc
	s_cbranch_execz .LBB0_1444
	s_mov_b32 s36, 1
	s_mov_b64 s[14:15], 0
	s_branch .LBB0_1435

; __device__ __forceinline__ unsigned xb_ld(unsigned* p)              { return __hip_atomic_load(p, __ATOMIC_RELAXED, __HIP_MEMORY_SCOPE_AGENT); }
; __device__ __forceinline__ unsigned xb_add(unsigned* p, unsigned v) { return __hip_atomic_fetch_add(p, v, __ATOMIC_RELAXED, __HIP_MEMORY_SCOPE_AGENT); }
; #define XB_SPIN(cond, bar) do { unsigned _sp = 0; while (cond) { __builtin_amdgcn_s_sleep(1); \
;     if ((++_sp & 255u) == 0u) { if (xb_ld(&(bar)[XB_TMO])) break; if (_sp > XB_SPIN_CAP) { atomicAdd(&(bar)[XB_TMO], 1u); break; } } } } while (0)
; __device__ __forceinline__ void xcd_barrier(const XcdBarrier& b) {
;     ...
;     const unsigned old = xb_add(&bar[XB_XSUB(bx)], 1u);
;     const unsigned gen = old / nloc;
;     if (old + 1u == (gen + 1u) * nloc) {
;       __builtin_amdgcn_fence(__ATOMIC_RELEASE, "agent");
;       asm volatile("s_waitcnt vmcnt(0)" ::: "memory");
;       const unsigned og = xb_add(&bar[XB_TOP], 1u);
;       const unsigned tg = og / nx;
;       if (og + 1u == (tg + 1u) * nx) xb_add(&bar[XB_TOPGEN], 1u);
;       else XB_SPIN(xb_ld(&bar[XB_TOPGEN]) == tg, bar);
;       __builtin_amdgcn_fence(__ATOMIC_ACQUIRE, "agent");
;       xb_add(&bar[XB_XGEN(bx)], 1u);
;       asm volatile("s_waitcnt vmcnt(0)" ::: "memory");
;     } else {
;       XB_SPIN(xb_ld(&bar[XB_XGEN(bx)]) == gen, bar);
.LBB0_1672:
	s_or_b64 exec, exec, s[12:13]
	v_cvt_f32_u32_e32 v5, v3
	s_waitcnt vmcnt(0)
	v_readfirstlane_b32 s10, v4
	v_sub_u32_e32 v4, 0, v3
	v_rcp_iflag_f32_e32 v5, v5
	v_add_u32_e32 v6, s10, v0
	v_mul_f32_e32 v5, 0x4f7ffffe, v5
	v_cvt_u32_f32_e32 v5, v5
	v_mul_lo_u32 v0, v4, v5
	v_mul_hi_u32 v0, v5, v0
	v_add_u32_e32 v0, v5, v0
	v_mul_hi_u32 v0, v6, v0
	v_mul_lo_u32 v4, v0, v3
	v_sub_u32_e32 v4, v6, v4
	v_add_u32_e32 v5, 1, v0
	v_cmp_ge_u32_e32 vcc, v4, v3
	s_nop 1
	v_cndmask_b32_e32 v0, v0, v5, vcc
	v_sub_u32_e32 v5, v4, v3
	v_cndmask_b32_e32 v4, v4, v5, vcc
	v_add_u32_e32 v5, 1, v0
	v_cmp_ge_u32_e32 vcc, v4, v3
	v_add_u32_e32 v4, 1, v6
	s_nop 0
	v_cndmask_b32_e32 v0, v0, v5, vcc
	v_mul_lo_u32 v5, v3, v0
	v_add_u32_e32 v3, v5, v3
	v_cmp_ne_u32_e32 vcc, v4, v3
	s_and_saveexec_b64 s[10:11], vcc
	s_xor_b64 s[10:11], exec, s[10:11]
	s_cbranch_execz .LBB0_1686
	s_movk_i32 s96, 0xd40
	s_lshl_b64 s[12:13], s[96:97], 2
	v_readlane_b32 s14, v240, 2
	v_readlane_b32 s15, v240, 3
	s_add_u32 s14, s14, s12
	s_addc_u32 s15, s15, s13
	s_waitcnt lgkmcnt(0)
	s_nop 1
	global_load_dword v2, v1, s[14:15] sc1
	s_waitcnt vmcnt(0)
	v_cmp_eq_u32_e32 vcc, v2, v0
	s_and_saveexec_b64 s[12:13], vcc
	s_cbranch_execz .LBB0_1685
	s_mov_b32 s36, 1
	s_mov_b64 s[80:81], 0
	s_branch .LBB0_1676

; __device__ __forceinline__ unsigned xb_ld(unsigned* p)              { return __hip_atomic_load(p, __ATOMIC_RELAXED, __HIP_MEMORY_SCOPE_AGENT); }
; __device__ __forceinline__ unsigned xb_add(unsigned* p, unsigned v) { return __hip_atomic_fetch_add(p, v, __ATOMIC_RELAXED, __HIP_MEMORY_SCOPE_AGENT); }
; #define XB_SPIN(cond, bar) do { unsigned _sp = 0; while (cond) { __builtin_amdgcn_s_sleep(1); \
;     if ((++_sp & 255u) == 0u) { if (xb_ld(&(bar)[XB_TMO])) break; if (_sp > XB_SPIN_CAP) { atomicAdd(&(bar)[XB_TMO], 1u); break; } } } } while (0)
; __device__ __forceinline__ void xcd_barrier(const XcdBarrier& b) {
;     ...
;     const unsigned old = xb_add(&bar[XB_XSUB(bx)], 1u);
;     const unsigned gen = old / nloc;
;     if (old + 1u == (gen + 1u) * nloc) {
;       __builtin_amdgcn_fence(__ATOMIC_RELEASE, "agent");
;       asm volatile("s_waitcnt vmcnt(0)" ::: "memory");
;       const unsigned og = xb_add(&bar[XB_TOP], 1u);
;       const unsigned tg = og / nx;
;       if (og + 1u == (tg + 1u) * nx) xb_add(&bar[XB_TOPGEN], 1u);
;       else XB_SPIN(xb_ld(&bar[XB_TOPGEN]) == tg, bar);
;       __builtin_amdgcn_fence(__ATOMIC_ACQUIRE, "agent");
;       xb_add(&bar[XB_XGEN(bx)], 1u);
;       asm volatile("s_waitcnt vmcnt(0)" ::: "memory");
;     } else {
;       XB_SPIN(xb_ld(&bar[XB_XGEN(bx)]) == gen, bar);
.LBB0_1798:
	s_or_b64 exec, exec, s[8:9]
	v_cvt_f32_u32_e32 v4, v2
	s_waitcnt vmcnt(0)
	v_readfirstlane_b32 s3, v3
	v_sub_u32_e32 v3, 0, v2
	v_rcp_iflag_f32_e32 v4, v4
	v_add_u32_e32 v5, s3, v1
	v_mul_f32_e32 v4, 0x4f7ffffe, v4
	v_cvt_u32_f32_e32 v4, v4
	v_mul_lo_u32 v1, v3, v4
	v_mul_hi_u32 v1, v4, v1
	v_add_u32_e32 v1, v4, v1
	v_mul_hi_u32 v1, v5, v1
	v_mul_lo_u32 v3, v1, v2
	v_sub_u32_e32 v3, v5, v3
	v_add_u32_e32 v4, 1, v1
	v_cmp_ge_u32_e32 vcc, v3, v2
	s_nop 1
	v_cndmask_b32_e32 v1, v1, v4, vcc
	v_sub_u32_e32 v4, v3, v2
	v_cndmask_b32_e32 v3, v3, v4, vcc
	v_add_u32_e32 v4, 1, v1
	v_cmp_ge_u32_e32 vcc, v3, v2
	v_add_u32_e32 v3, 1, v5
	s_nop 0
	v_cndmask_b32_e32 v1, v1, v4, vcc
	v_mul_lo_u32 v4, v2, v1
	v_add_u32_e32 v2, v4, v2
	v_cmp_ne_u32_e32 vcc, v3, v2
	s_and_saveexec_b64 s[4:5], vcc
	s_xor_b64 s[6:7], exec, s[4:5]
	s_cbranch_execz .LBB0_1812
	s_movk_i32 s4, 0xd40
	s_mov_b32 s5, 0
	s_lshl_b64 s[4:5], s[4:5], 2
	v_readlane_b32 s8, v240, 2
	v_readlane_b32 s9, v240, 3
	s_add_u32 s10, s8, s4
	s_addc_u32 s11, s9, s5
	s_waitcnt lgkmcnt(0)
	v_mov_b32_e32 v0, 0
	global_load_dword v2, v0, s[10:11] sc1
	s_waitcnt vmcnt(0)
	v_cmp_eq_u32_e32 vcc, v2, v1
	s_and_saveexec_b64 s[8:9], vcc
	s_cbranch_execz .LBB0_1811
	s_mov_b32 s3, 1
	s_mov_b64 s[12:13], 0
	s_branch .LBB0_1802

; __device__ __forceinline__ unsigned xb_ld(unsigned* p)              { return __hip_atomic_load(p, __ATOMIC_RELAXED, __HIP_MEMORY_SCOPE_AGENT); }
; __device__ __forceinline__ unsigned xb_add(unsigned* p, unsigned v) { return __hip_atomic_fetch_add(p, v, __ATOMIC_RELAXED, __HIP_MEMORY_SCOPE_AGENT); }
; #define XB_SPIN(cond, bar) do { unsigned _sp = 0; while (cond) { __builtin_amdgcn_s_sleep(1); \
;     if ((++_sp & 255u) == 0u) { if (xb_ld(&(bar)[XB_TMO])) break; if (_sp > XB_SPIN_CAP) { atomicAdd(&(bar)[XB_TMO], 1u); break; } } } } while (0)
; __device__ __forceinline__ void xcd_barrier(const XcdBarrier& b) {
;     ...
;     const unsigned old = xb_add(&bar[XB_XSUB(bx)], 1u);
;     const unsigned gen = old / nloc;
;     if (old + 1u == (gen + 1u) * nloc) {
;       __builtin_amdgcn_fence(__ATOMIC_RELEASE, "agent");
;       asm volatile("s_waitcnt vmcnt(0)" ::: "memory");
;       const unsigned og = xb_add(&bar[XB_TOP], 1u);
;       const unsigned tg = og / nx;
;       if (og + 1u == (tg + 1u) * nx) xb_add(&bar[XB_TOPGEN], 1u);
;       else XB_SPIN(xb_ld(&bar[XB_TOPGEN]) == tg, bar);
;       __builtin_amdgcn_fence(__ATOMIC_ACQUIRE, "agent");
;       xb_add(&bar[XB_XGEN(bx)], 1u);
;       asm volatile("s_waitcnt vmcnt(0)" ::: "memory");
;     } else {
;       XB_SPIN(xb_ld(&bar[XB_XGEN(bx)]) == gen, bar);
.LBB0_1878:
	s_or_b64 exec, exec, s[6:7]
	v_cvt_f32_u32_e32 v4, v2
	s_waitcnt vmcnt(0)
	v_readfirstlane_b32 s3, v3
	v_sub_u32_e32 v3, 0, v2
	v_rcp_iflag_f32_e32 v4, v4
	v_add_u32_e32 v5, s3, v1
	v_mul_f32_e32 v4, 0x4f7ffffe, v4
	v_cvt_u32_f32_e32 v4, v4
	v_mul_lo_u32 v1, v3, v4
	v_mul_hi_u32 v1, v4, v1
	v_add_u32_e32 v1, v4, v1
	v_mul_hi_u32 v1, v5, v1
	v_mul_lo_u32 v3, v1, v2
	v_sub_u32_e32 v3, v5, v3
	v_add_u32_e32 v4, 1, v1
	v_cmp_ge_u32_e32 vcc, v3, v2
	s_nop 1
	v_cndmask_b32_e32 v1, v1, v4, vcc
	v_sub_u32_e32 v4, v3, v2
	v_cndmask_b32_e32 v3, v3, v4, vcc
	v_add_u32_e32 v4, 1, v1
	v_cmp_ge_u32_e32 vcc, v3, v2
	v_add_u32_e32 v3, 1, v5
	s_nop 0
	v_cndmask_b32_e32 v1, v1, v4, vcc
	v_mul_lo_u32 v4, v2, v1
	v_add_u32_e32 v2, v4, v2
	v_cmp_ne_u32_e32 vcc, v3, v2
	s_and_saveexec_b64 s[4:5], vcc
	s_xor_b64 s[4:5], exec, s[4:5]
	s_cbranch_execz .LBB0_1892
	s_movk_i32 s6, 0xd40
	s_mov_b32 s7, 0
	s_lshl_b64 s[6:7], s[6:7], 2
	v_readlane_b32 s8, v240, 2
	v_readlane_b32 s9, v240, 3
	s_add_u32 s8, s8, s6
	s_addc_u32 s9, s9, s7
	s_waitcnt lgkmcnt(0)
	v_mov_b32_e32 v0, 0
	s_nop 0
	global_load_dword v2, v0, s[8:9] sc1
	s_waitcnt vmcnt(0)
	v_cmp_eq_u32_e32 vcc, v2, v1
	s_and_saveexec_b64 s[6:7], vcc
	s_cbranch_execz .LBB0_1891
	s_mov_b32 s3, 1
	s_mov_b64 s[10:11], 0
	s_branch .LBB0_1882
